# GEMM1 gate epilogue: 16x16 in-register transpose (permlane32/16 swap + DPP) so each store writes one 64B piece into each of 16 1KB chunks; same layout; + no entry grid.sync
# baseline (speedup 1.0000x reference)
; __device__ __forceinline__ float sigm(float v) { return __builtin_amdgcn_rcpf(1.0f + __builtin_amdgcn_exp2f(-LOG2E * v)); }
; __device__ __forceinline__ unsigned cvt_pk_bf16(float lo, float hi) { f32x2_t v = {lo, hi}; bf16x2_t b = __builtin_convertvector(v, bf16x2_t); return __builtin_bit_cast(unsigned, b); }
; #define EPI_FENCE() asm volatile("" ::: "memory")
; #define EPI_LANE() int t__ = threadIdx.x; asm volatile("" : "+v"(t__)); const int wid__ = __builtin_amdgcn_readfirstlane(t__ >> 6); wr = wid__ >> 2; wc = wid__ & 3; fr = t__ & 15; fq = (t__ & 63) >> 4
; template <int MODE> __device__ __forceinline__ float actf(float v) {
;     if (MODE == 1) return v * sigm(v);
;     if (MODE == 2) return fminf(1.0f + __builtin_amdgcn_exp2f(-LOG2E * v), 1e30f);
;     if (MODE == 3) return v * QSCALE;
;     return v;
; }
;     template <int MODE> __device__ __forceinline__ void run(const f32x4 (&acc)[2][2][4][2], const Unit& u, int wr, int wc, int fr, int fq) const {
;         EPI_LANE();
;         const int pn = u.pn, colt = pn * BM, t = colt >> 9;
;         char* base = (MODE == 2) ? (char*)(O + (size_t)6 * ((size_t)MTOK * 512)) + ((size_t)(((pn - 12) * 128 + u.pm) * 8 + wid__)) * 16384
;                                  : (char*)(O + (size_t)t * ((size_t)MTOK * 512) + (size_t)u.pm * BM * 512 + (colt & 511));
;         unsigned off0 = (MODE == 2) ? (unsigned)((t__ & 63) * 16) : (unsigned)((wr * 64 + fr) * 512 + wc * 32 + 8 * fq) * 2u; asm volatile("" : "+v"(off0));
; #pragma unroll
;         for (int bj = 0; bj < 2; ++bj) {
; #pragma unroll
;             for (int ai = 0; ai < 2; ++ai)
; #pragma unroll
;                 for (int m = 0; m < 4; ++m) { const unsigned off = off0 + ((MODE == 2) ? (unsigned)(((ai * 4 + m) * 2 + bj) * 1024) : (unsigned)((ai * HALF + m * 16) * 512 + bj * HALF) * 2u);
;                     const f32x4 v0 = acc[ai][bj][m][0], v1 = acc[ai][bj][m][1];
;                     u32x4 w; w.x = cvt_pk_bf16(actf<MODE>(v0[0]), actf<MODE>(v0[1])); w.y = cvt_pk_bf16(actf<MODE>(v0[2]), actf<MODE>(v0[3]));
;                     w.z = cvt_pk_bf16(actf<MODE>(v1[0]), actf<MODE>(v1[1])); w.w = cvt_pk_bf16(actf<MODE>(v1[2]), actf<MODE>(v1[3]));
;                     *(u32x4*)(base + off) = w; }
;             EPI_FENCE();
;         }
.LBB0_403:
	v_mov_b32_e32 v142, v212
	s_lshl_b32 s60, s72, 7
	s_add_i32 s60, s60, s54
	v_readfirstlane_b32 s55, v142
	s_lshl_b32 s54, s60, 3
	s_ashr_i32 s55, s55, 6
	s_add_i32 s54, s54, s55
	s_addk_i32 s54, 0xd000
	s_ashr_i32 s55, s54, 31
	s_lshl_b64 s[54:55], s[54:55], 14
	v_lshlrev_b32_e32 v142, 4, v142
	s_add_u32 s54, s33, s54
	s_addc_u32 s55, s37, s55
	v_and_b32_e32 v142, 0x3f0, v142
	v_add_u32_e32 v144, 0x400, v142
	v_add_u32_e32 v145, 0x800, v142
	v_add_u32_e32 v146, 0xc00, v142
	v_add_u32_e32 v147, 0x1000, v142
	v_add_u32_e32 v148, 0x1400, v142
	v_add_u32_e32 v149, 0x1800, v142
	v_add_u32_e32 v150, 0x1c00, v142
	v_add_u32_e32 v151, 0x2000, v142
	v_add_u32_e32 v152, 0x2400, v142
	v_add_u32_e32 v153, 0x2800, v142
	v_add_u32_e32 v154, 0x2c00, v142
	v_add_u32_e32 v155, 0x3000, v142
	v_add_u32_e32 v156, 0x3400, v142
	v_add_u32_e32 v157, 0x3800, v142
	v_add_u32_e32 v158, 0x3c00, v142
	v_mul_f32_e32 v126, 0xbfb8aa3b, v126
	v_mul_f32_e32 v127, 0xbfb8aa3b, v127
	v_mul_f32_e32 v128, 0xbfb8aa3b, v128
	v_mul_f32_e32 v129, 0xbfb8aa3b, v129
	v_mul_f32_e32 v122, 0xbfb8aa3b, v122
	v_mul_f32_e32 v123, 0xbfb8aa3b, v123
	v_mul_f32_e32 v124, 0xbfb8aa3b, v124
	v_mul_f32_e32 v125, 0xbfb8aa3b, v125
	v_exp_f32_e32 v126, v126
	v_exp_f32_e32 v127, v127
	v_exp_f32_e32 v128, v128
	v_exp_f32_e32 v129, v129
	v_exp_f32_e32 v122, v122
	v_exp_f32_e32 v123, v123
	v_exp_f32_e32 v124, v124
	v_exp_f32_e32 v125, v125
	v_add_f32_e32 v126, 1.0, v126
	v_add_f32_e32 v127, 1.0, v127
	v_add_f32_e32 v128, 1.0, v128
	v_add_f32_e32 v129, 1.0, v129
	v_add_f32_e32 v122, 1.0, v122
	v_add_f32_e32 v123, 1.0, v123
	v_add_f32_e32 v124, 1.0, v124
	v_add_f32_e32 v125, 1.0, v125
	v_min_f32_e32 v126, 0x7149f2ca, v126
	v_min_f32_e32 v127, 0x7149f2ca, v127
	v_min_f32_e32 v128, 0x7149f2ca, v128
	v_min_f32_e32 v129, 0x7149f2ca, v129
	v_min_f32_e32 v122, 0x7149f2ca, v122
	v_min_f32_e32 v123, 0x7149f2ca, v123
	v_min_f32_e32 v124, 0x7149f2ca, v124
	v_min_f32_e32 v125, 0x7149f2ca, v125
	v_cvt_pk_bf16_f32 v126, v126, v127
	v_cvt_pk_bf16_f32 v127, v128, v129
	v_cvt_pk_bf16_f32 v128, v122, v123
	v_cvt_pk_bf16_f32 v129, v124, v125
	v_mul_f32_e32 v68, 0xbfb8aa3b, v68
	v_mul_f32_e32 v69, 0xbfb8aa3b, v69
	v_mul_f32_e32 v70, 0xbfb8aa3b, v70
	v_mul_f32_e32 v71, 0xbfb8aa3b, v71
	v_mul_f32_e32 v64, 0xbfb8aa3b, v64
	v_mul_f32_e32 v65, 0xbfb8aa3b, v65
	v_mul_f32_e32 v66, 0xbfb8aa3b, v66
	v_mul_f32_e32 v67, 0xbfb8aa3b, v67
	v_exp_f32_e32 v68, v68
	v_exp_f32_e32 v69, v69
	v_exp_f32_e32 v70, v70
	v_exp_f32_e32 v71, v71
	v_exp_f32_e32 v64, v64
	v_exp_f32_e32 v65, v65
	v_exp_f32_e32 v66, v66
	v_exp_f32_e32 v67, v67
	v_add_f32_e32 v68, 1.0, v68
	v_add_f32_e32 v69, 1.0, v69
	v_add_f32_e32 v70, 1.0, v70
	v_add_f32_e32 v71, 1.0, v71
	v_add_f32_e32 v64, 1.0, v64
	v_add_f32_e32 v65, 1.0, v65
	v_add_f32_e32 v66, 1.0, v66
	v_add_f32_e32 v67, 1.0, v67
	v_min_f32_e32 v68, 0x7149f2ca, v68
	v_min_f32_e32 v69, 0x7149f2ca, v69
	v_min_f32_e32 v70, 0x7149f2ca, v70
	v_min_f32_e32 v71, 0x7149f2ca, v71
	v_min_f32_e32 v64, 0x7149f2ca, v64
	v_min_f32_e32 v65, 0x7149f2ca, v65
	v_min_f32_e32 v66, 0x7149f2ca, v66
	v_min_f32_e32 v67, 0x7149f2ca, v67
	v_cvt_pk_bf16_f32 v68, v68, v69
	v_cvt_pk_bf16_f32 v69, v70, v71
	v_cvt_pk_bf16_f32 v70, v64, v65
	v_cvt_pk_bf16_f32 v71, v66, v67
	v_mul_f32_e32 v118, 0xbfb8aa3b, v118
	v_mul_f32_e32 v119, 0xbfb8aa3b, v119
	v_mul_f32_e32 v120, 0xbfb8aa3b, v120
	v_mul_f32_e32 v121, 0xbfb8aa3b, v121
	v_mul_f32_e32 v114, 0xbfb8aa3b, v114
	v_mul_f32_e32 v115, 0xbfb8aa3b, v115
	v_mul_f32_e32 v116, 0xbfb8aa3b, v116
	v_mul_f32_e32 v117, 0xbfb8aa3b, v117
	v_exp_f32_e32 v118, v118
	v_exp_f32_e32 v119, v119
	v_exp_f32_e32 v120, v120
	v_exp_f32_e32 v121, v121
	v_exp_f32_e32 v114, v114
	v_exp_f32_e32 v115, v115
	v_exp_f32_e32 v116, v116
	v_exp_f32_e32 v117, v117
	v_add_f32_e32 v118, 1.0, v118
	v_add_f32_e32 v119, 1.0, v119
	v_add_f32_e32 v120, 1.0, v120
	v_add_f32_e32 v121, 1.0, v121
	v_add_f32_e32 v114, 1.0, v114
	v_add_f32_e32 v115, 1.0, v115
	v_add_f32_e32 v116, 1.0, v116
	v_add_f32_e32 v117, 1.0, v117
	v_min_f32_e32 v118, 0x7149f2ca, v118
	v_min_f32_e32 v119, 0x7149f2ca, v119
	v_min_f32_e32 v120, 0x7149f2ca, v120
	v_min_f32_e32 v121, 0x7149f2ca, v121
	v_min_f32_e32 v114, 0x7149f2ca, v114
	v_min_f32_e32 v115, 0x7149f2ca, v115
	v_min_f32_e32 v116, 0x7149f2ca, v116
	v_min_f32_e32 v117, 0x7149f2ca, v117
	v_cvt_pk_bf16_f32 v118, v118, v119
	v_cvt_pk_bf16_f32 v119, v120, v121
	v_cvt_pk_bf16_f32 v120, v114, v115
	v_cvt_pk_bf16_f32 v121, v116, v117
	v_mul_f32_e32 v60, 0xbfb8aa3b, v60
	v_mul_f32_e32 v61, 0xbfb8aa3b, v61
	v_mul_f32_e32 v62, 0xbfb8aa3b, v62
	v_mul_f32_e32 v63, 0xbfb8aa3b, v63
	v_mul_f32_e32 v56, 0xbfb8aa3b, v56
	v_mul_f32_e32 v57, 0xbfb8aa3b, v57
	v_mul_f32_e32 v58, 0xbfb8aa3b, v58
	v_mul_f32_e32 v59, 0xbfb8aa3b, v59
	v_exp_f32_e32 v60, v60
	v_exp_f32_e32 v61, v61
	v_exp_f32_e32 v62, v62
	v_exp_f32_e32 v63, v63
	v_exp_f32_e32 v56, v56
	v_exp_f32_e32 v57, v57
	v_exp_f32_e32 v58, v58
	v_exp_f32_e32 v59, v59
	v_add_f32_e32 v60, 1.0, v60
	v_add_f32_e32 v61, 1.0, v61
	v_add_f32_e32 v62, 1.0, v62
	v_add_f32_e32 v63, 1.0, v63
	v_add_f32_e32 v56, 1.0, v56
	v_add_f32_e32 v57, 1.0, v57
	v_add_f32_e32 v58, 1.0, v58
	v_add_f32_e32 v59, 1.0, v59
	v_min_f32_e32 v60, 0x7149f2ca, v60
	v_min_f32_e32 v61, 0x7149f2ca, v61
	v_min_f32_e32 v62, 0x7149f2ca, v62
	v_min_f32_e32 v63, 0x7149f2ca, v63
	v_min_f32_e32 v56, 0x7149f2ca, v56
	v_min_f32_e32 v57, 0x7149f2ca, v57
	v_min_f32_e32 v58, 0x7149f2ca, v58
	v_min_f32_e32 v59, 0x7149f2ca, v59
	v_cvt_pk_bf16_f32 v60, v60, v61
	v_cvt_pk_bf16_f32 v61, v62, v63
	v_cvt_pk_bf16_f32 v62, v56, v57
	v_cvt_pk_bf16_f32 v63, v58, v59
	v_mul_f32_e32 v110, 0xbfb8aa3b, v110
	v_mul_f32_e32 v111, 0xbfb8aa3b, v111
; __device__ __forceinline__ float sigm(float v) { return __builtin_amdgcn_rcpf(1.0f + __builtin_amdgcn_exp2f(-LOG2E * v)); }
; __device__ __forceinline__ unsigned cvt_pk_bf16(float lo, float hi) { f32x2_t v = {lo, hi}; bf16x2_t b = __builtin_convertvector(v, bf16x2_t); return __builtin_bit_cast(unsigned, b); }
; template <int MODE> __device__ __forceinline__ float actf(float v) {
;     if (MODE == 1) return v * sigm(v);
;     if (MODE == 2) return fminf(1.0f + __builtin_amdgcn_exp2f(-LOG2E * v), 1e30f);
;     if (MODE == 3) return v * QSCALE;
;     return v;
; }
;     template <int MODE> __device__ __forceinline__ void run(const f32x4 (&acc)[2][2][4][2], const Unit& u, int wr, int wc, int fr, int fq) const {
;     ...
;                 for (int m = 0; m < 4; ++m) { const unsigned off = off0 + ((MODE == 2) ? (unsigned)(((ai * 4 + m) * 2 + bj) * 1024) : (unsigned)((ai * HALF + m * 16) * 512 + bj * HALF) * 2u);
;                     const f32x4 v0 = acc[ai][bj][m][0], v1 = acc[ai][bj][m][1];
;                     u32x4 w; w.x = cvt_pk_bf16(actf<MODE>(v0[0]), actf<MODE>(v0[1])); w.y = cvt_pk_bf16(actf<MODE>(v0[2]), actf<MODE>(v0[3]));
;                     w.z = cvt_pk_bf16(actf<MODE>(v1[0]), actf<MODE>(v1[1])); w.w = cvt_pk_bf16(actf<MODE>(v1[2]), actf<MODE>(v1[3]));
;                     *(u32x4*)(base + off) = w; }
	v_mul_f32_e32 v112, 0xbfb8aa3b, v112
	v_mul_f32_e32 v113, 0xbfb8aa3b, v113
	v_mul_f32_e32 v106, 0xbfb8aa3b, v106
	v_mul_f32_e32 v107, 0xbfb8aa3b, v107
	v_mul_f32_e32 v108, 0xbfb8aa3b, v108
	v_mul_f32_e32 v109, 0xbfb8aa3b, v109
	v_exp_f32_e32 v110, v110
	v_exp_f32_e32 v111, v111
	v_exp_f32_e32 v112, v112
	v_exp_f32_e32 v113, v113
	v_exp_f32_e32 v106, v106
	v_exp_f32_e32 v107, v107
	v_exp_f32_e32 v108, v108
	v_exp_f32_e32 v109, v109
	v_add_f32_e32 v110, 1.0, v110
	v_add_f32_e32 v111, 1.0, v111
	v_add_f32_e32 v112, 1.0, v112
	v_add_f32_e32 v113, 1.0, v113
	v_add_f32_e32 v106, 1.0, v106
	v_add_f32_e32 v107, 1.0, v107
	v_add_f32_e32 v108, 1.0, v108
	v_add_f32_e32 v109, 1.0, v109
	v_min_f32_e32 v110, 0x7149f2ca, v110
	v_min_f32_e32 v111, 0x7149f2ca, v111
	v_min_f32_e32 v112, 0x7149f2ca, v112
	v_min_f32_e32 v113, 0x7149f2ca, v113
	v_min_f32_e32 v106, 0x7149f2ca, v106
	v_min_f32_e32 v107, 0x7149f2ca, v107
	v_min_f32_e32 v108, 0x7149f2ca, v108
	v_min_f32_e32 v109, 0x7149f2ca, v109
	v_cvt_pk_bf16_f32 v110, v110, v111
	v_cvt_pk_bf16_f32 v111, v112, v113
	v_cvt_pk_bf16_f32 v112, v106, v107
	v_cvt_pk_bf16_f32 v113, v108, v109
	v_mul_f32_e32 v52, 0xbfb8aa3b, v52
	v_mul_f32_e32 v53, 0xbfb8aa3b, v53
	v_mul_f32_e32 v54, 0xbfb8aa3b, v54
	v_mul_f32_e32 v55, 0xbfb8aa3b, v55
	v_mul_f32_e32 v48, 0xbfb8aa3b, v48
	v_mul_f32_e32 v49, 0xbfb8aa3b, v49
	v_mul_f32_e32 v50, 0xbfb8aa3b, v50
	v_mul_f32_e32 v51, 0xbfb8aa3b, v51
	v_exp_f32_e32 v52, v52
	v_exp_f32_e32 v53, v53
	v_exp_f32_e32 v54, v54
	v_exp_f32_e32 v55, v55
	v_exp_f32_e32 v48, v48
	v_exp_f32_e32 v49, v49
	v_exp_f32_e32 v50, v50
	v_exp_f32_e32 v51, v51
	v_add_f32_e32 v52, 1.0, v52
	v_add_f32_e32 v53, 1.0, v53
	v_add_f32_e32 v54, 1.0, v54
	v_add_f32_e32 v55, 1.0, v55
	v_add_f32_e32 v48, 1.0, v48
	v_add_f32_e32 v49, 1.0, v49
	v_add_f32_e32 v50, 1.0, v50
	v_add_f32_e32 v51, 1.0, v51
	v_min_f32_e32 v52, 0x7149f2ca, v52
	v_min_f32_e32 v53, 0x7149f2ca, v53
	v_min_f32_e32 v54, 0x7149f2ca, v54
	v_min_f32_e32 v55, 0x7149f2ca, v55
	v_min_f32_e32 v48, 0x7149f2ca, v48
	v_min_f32_e32 v49, 0x7149f2ca, v49
	v_min_f32_e32 v50, 0x7149f2ca, v50
	v_min_f32_e32 v51, 0x7149f2ca, v51
	v_cvt_pk_bf16_f32 v52, v52, v53
	v_cvt_pk_bf16_f32 v53, v54, v55
	v_cvt_pk_bf16_f32 v54, v48, v49
	v_cvt_pk_bf16_f32 v55, v50, v51
	v_mul_f32_e32 v102, 0xbfb8aa3b, v102
	v_mul_f32_e32 v103, 0xbfb8aa3b, v103
	v_mul_f32_e32 v104, 0xbfb8aa3b, v104
	v_mul_f32_e32 v105, 0xbfb8aa3b, v105
	v_mul_f32_e32 v98, 0xbfb8aa3b, v98
	v_mul_f32_e32 v99, 0xbfb8aa3b, v99
	v_mul_f32_e32 v100, 0xbfb8aa3b, v100
	v_mul_f32_e32 v101, 0xbfb8aa3b, v101
	v_exp_f32_e32 v102, v102
	v_exp_f32_e32 v103, v103
	v_exp_f32_e32 v104, v104
	v_exp_f32_e32 v105, v105
	v_exp_f32_e32 v98, v98
	v_exp_f32_e32 v99, v99
	v_exp_f32_e32 v100, v100
	v_exp_f32_e32 v101, v101
	v_add_f32_e32 v102, 1.0, v102
	v_add_f32_e32 v103, 1.0, v103
	v_add_f32_e32 v104, 1.0, v104
	v_add_f32_e32 v105, 1.0, v105
	v_add_f32_e32 v98, 1.0, v98
	v_add_f32_e32 v99, 1.0, v99
	v_add_f32_e32 v100, 1.0, v100
	v_add_f32_e32 v101, 1.0, v101
	v_min_f32_e32 v102, 0x7149f2ca, v102
	v_min_f32_e32 v103, 0x7149f2ca, v103
	v_min_f32_e32 v104, 0x7149f2ca, v104
	v_min_f32_e32 v105, 0x7149f2ca, v105
	v_min_f32_e32 v98, 0x7149f2ca, v98
	v_min_f32_e32 v99, 0x7149f2ca, v99
	v_min_f32_e32 v100, 0x7149f2ca, v100
	v_min_f32_e32 v101, 0x7149f2ca, v101
	v_cvt_pk_bf16_f32 v102, v102, v103
	v_cvt_pk_bf16_f32 v103, v104, v105
	v_cvt_pk_bf16_f32 v104, v98, v99
	v_cvt_pk_bf16_f32 v105, v100, v101
	v_mul_f32_e32 v44, 0xbfb8aa3b, v44
	v_mul_f32_e32 v45, 0xbfb8aa3b, v45
	v_mul_f32_e32 v46, 0xbfb8aa3b, v46
	v_mul_f32_e32 v47, 0xbfb8aa3b, v47
	v_mul_f32_e32 v40, 0xbfb8aa3b, v40
	v_mul_f32_e32 v41, 0xbfb8aa3b, v41
	v_mul_f32_e32 v42, 0xbfb8aa3b, v42
	v_mul_f32_e32 v43, 0xbfb8aa3b, v43
	v_exp_f32_e32 v44, v44
	v_exp_f32_e32 v45, v45
	v_exp_f32_e32 v46, v46
	v_exp_f32_e32 v47, v47
	v_exp_f32_e32 v40, v40
	v_exp_f32_e32 v41, v41
	v_exp_f32_e32 v42, v42
	v_exp_f32_e32 v43, v43
	v_add_f32_e32 v44, 1.0, v44
	v_add_f32_e32 v45, 1.0, v45
	v_add_f32_e32 v46, 1.0, v46
	v_add_f32_e32 v47, 1.0, v47
	v_add_f32_e32 v40, 1.0, v40
	v_add_f32_e32 v41, 1.0, v41
	v_add_f32_e32 v42, 1.0, v42
	v_add_f32_e32 v43, 1.0, v43
	v_min_f32_e32 v44, 0x7149f2ca, v44
	v_min_f32_e32 v45, 0x7149f2ca, v45
	v_min_f32_e32 v46, 0x7149f2ca, v46
	v_min_f32_e32 v47, 0x7149f2ca, v47
	v_min_f32_e32 v40, 0x7149f2ca, v40
	v_min_f32_e32 v41, 0x7149f2ca, v41
	v_min_f32_e32 v42, 0x7149f2ca, v42
	v_min_f32_e32 v43, 0x7149f2ca, v43
	v_cvt_pk_bf16_f32 v44, v44, v45
	v_cvt_pk_bf16_f32 v45, v46, v47
	v_cvt_pk_bf16_f32 v46, v40, v41
	v_cvt_pk_bf16_f32 v47, v42, v43
	v_mul_f32_e32 v92, 0xbfb8aa3b, v92
	v_mul_f32_e32 v93, 0xbfb8aa3b, v93
	v_mul_f32_e32 v94, 0xbfb8aa3b, v94
	v_mul_f32_e32 v95, 0xbfb8aa3b, v95
	v_mul_f32_e32 v88, 0xbfb8aa3b, v88
	v_mul_f32_e32 v89, 0xbfb8aa3b, v89
	v_mul_f32_e32 v90, 0xbfb8aa3b, v90
	v_mul_f32_e32 v91, 0xbfb8aa3b, v91
	v_exp_f32_e32 v92, v92
	v_exp_f32_e32 v93, v93
	v_exp_f32_e32 v94, v94
	v_exp_f32_e32 v95, v95
	v_exp_f32_e32 v88, v88
	v_exp_f32_e32 v89, v89
	v_exp_f32_e32 v90, v90
	v_exp_f32_e32 v91, v91
	v_add_f32_e32 v92, 1.0, v92
	v_add_f32_e32 v93, 1.0, v93
	v_add_f32_e32 v94, 1.0, v94
	v_add_f32_e32 v95, 1.0, v95
	v_add_f32_e32 v88, 1.0, v88
	v_add_f32_e32 v89, 1.0, v89
	v_add_f32_e32 v90, 1.0, v90
	v_add_f32_e32 v91, 1.0, v91
	v_min_f32_e32 v92, 0x7149f2ca, v92
	v_min_f32_e32 v93, 0x7149f2ca, v93
	v_min_f32_e32 v94, 0x7149f2ca, v94
	v_min_f32_e32 v95, 0x7149f2ca, v95
	v_min_f32_e32 v88, 0x7149f2ca, v88
	v_min_f32_e32 v89, 0x7149f2ca, v89
	v_min_f32_e32 v90, 0x7149f2ca, v90
	v_min_f32_e32 v91, 0x7149f2ca, v91
	v_cvt_pk_bf16_f32 v92, v92, v93
	v_cvt_pk_bf16_f32 v93, v94, v95
; __device__ __forceinline__ float sigm(float v) { return __builtin_amdgcn_rcpf(1.0f + __builtin_amdgcn_exp2f(-LOG2E * v)); }
; __device__ __forceinline__ unsigned cvt_pk_bf16(float lo, float hi) { f32x2_t v = {lo, hi}; bf16x2_t b = __builtin_convertvector(v, bf16x2_t); return __builtin_bit_cast(unsigned, b); }
; template <int MODE> __device__ __forceinline__ float actf(float v) {
;     if (MODE == 1) return v * sigm(v);
;     if (MODE == 2) return fminf(1.0f + __builtin_amdgcn_exp2f(-LOG2E * v), 1e30f);
;     if (MODE == 3) return v * QSCALE;
;     return v;
; }
;     template <int MODE> __device__ __forceinline__ void run(const f32x4 (&acc)[2][2][4][2], const Unit& u, int wr, int wc, int fr, int fq) const {
;     ...
;                 for (int m = 0; m < 4; ++m) { const unsigned off = off0 + ((MODE == 2) ? (unsigned)(((ai * 4 + m) * 2 + bj) * 1024) : (unsigned)((ai * HALF + m * 16) * 512 + bj * HALF) * 2u);
;                     const f32x4 v0 = acc[ai][bj][m][0], v1 = acc[ai][bj][m][1];
;                     u32x4 w; w.x = cvt_pk_bf16(actf<MODE>(v0[0]), actf<MODE>(v0[1])); w.y = cvt_pk_bf16(actf<MODE>(v0[2]), actf<MODE>(v0[3]));
;                     w.z = cvt_pk_bf16(actf<MODE>(v1[0]), actf<MODE>(v1[1])); w.w = cvt_pk_bf16(actf<MODE>(v1[2]), actf<MODE>(v1[3]));
;                     *(u32x4*)(base + off) = w; }
	v_cvt_pk_bf16_f32 v94, v88, v89
	v_cvt_pk_bf16_f32 v95, v90, v91
	v_mul_f32_e32 v36, 0xbfb8aa3b, v36
	v_mul_f32_e32 v37, 0xbfb8aa3b, v37
	v_mul_f32_e32 v38, 0xbfb8aa3b, v38
	v_mul_f32_e32 v39, 0xbfb8aa3b, v39
	v_mul_f32_e32 v32, 0xbfb8aa3b, v32
	v_mul_f32_e32 v33, 0xbfb8aa3b, v33
	v_mul_f32_e32 v34, 0xbfb8aa3b, v34
	v_mul_f32_e32 v35, 0xbfb8aa3b, v35
	v_exp_f32_e32 v36, v36
	v_exp_f32_e32 v37, v37
	v_exp_f32_e32 v38, v38
	v_exp_f32_e32 v39, v39
	v_exp_f32_e32 v32, v32
	v_exp_f32_e32 v33, v33
	v_exp_f32_e32 v34, v34
	v_exp_f32_e32 v35, v35
	v_add_f32_e32 v36, 1.0, v36
	v_add_f32_e32 v37, 1.0, v37
	v_add_f32_e32 v38, 1.0, v38
	v_add_f32_e32 v39, 1.0, v39
	v_add_f32_e32 v32, 1.0, v32
	v_add_f32_e32 v33, 1.0, v33
	v_add_f32_e32 v34, 1.0, v34
	v_add_f32_e32 v35, 1.0, v35
	v_min_f32_e32 v36, 0x7149f2ca, v36
	v_min_f32_e32 v37, 0x7149f2ca, v37
	v_min_f32_e32 v38, 0x7149f2ca, v38
	v_min_f32_e32 v39, 0x7149f2ca, v39
	v_min_f32_e32 v32, 0x7149f2ca, v32
	v_min_f32_e32 v33, 0x7149f2ca, v33
	v_min_f32_e32 v34, 0x7149f2ca, v34
	v_min_f32_e32 v35, 0x7149f2ca, v35
	v_cvt_pk_bf16_f32 v36, v36, v37
	v_cvt_pk_bf16_f32 v37, v38, v39
	v_cvt_pk_bf16_f32 v38, v32, v33
	v_cvt_pk_bf16_f32 v39, v34, v35
	v_mul_f32_e32 v84, 0xbfb8aa3b, v84
	v_mul_f32_e32 v85, 0xbfb8aa3b, v85
	v_mul_f32_e32 v86, 0xbfb8aa3b, v86
	v_mul_f32_e32 v87, 0xbfb8aa3b, v87
	v_mul_f32_e32 v80, 0xbfb8aa3b, v80
	v_mul_f32_e32 v81, 0xbfb8aa3b, v81
	v_mul_f32_e32 v82, 0xbfb8aa3b, v82
	v_mul_f32_e32 v83, 0xbfb8aa3b, v83
	v_exp_f32_e32 v84, v84
	v_exp_f32_e32 v85, v85
	v_exp_f32_e32 v86, v86
	v_exp_f32_e32 v87, v87
	v_exp_f32_e32 v80, v80
	v_exp_f32_e32 v81, v81
	v_exp_f32_e32 v82, v82
	v_exp_f32_e32 v83, v83
	v_add_f32_e32 v84, 1.0, v84
	v_add_f32_e32 v85, 1.0, v85
	v_add_f32_e32 v86, 1.0, v86
	v_add_f32_e32 v87, 1.0, v87
	v_add_f32_e32 v80, 1.0, v80
	v_add_f32_e32 v81, 1.0, v81
	v_add_f32_e32 v82, 1.0, v82
	v_add_f32_e32 v83, 1.0, v83
	v_min_f32_e32 v84, 0x7149f2ca, v84
	v_min_f32_e32 v85, 0x7149f2ca, v85
	v_min_f32_e32 v86, 0x7149f2ca, v86
	v_min_f32_e32 v87, 0x7149f2ca, v87
	v_min_f32_e32 v80, 0x7149f2ca, v80
	v_min_f32_e32 v81, 0x7149f2ca, v81
	v_min_f32_e32 v82, 0x7149f2ca, v82
	v_min_f32_e32 v83, 0x7149f2ca, v83
	v_cvt_pk_bf16_f32 v84, v84, v85
	v_cvt_pk_bf16_f32 v85, v86, v87
	v_cvt_pk_bf16_f32 v86, v80, v81
	v_cvt_pk_bf16_f32 v87, v82, v83
	v_mul_f32_e32 v28, 0xbfb8aa3b, v28
	v_mul_f32_e32 v29, 0xbfb8aa3b, v29
	v_mul_f32_e32 v30, 0xbfb8aa3b, v30
	v_mul_f32_e32 v31, 0xbfb8aa3b, v31
	v_mul_f32_e32 v24, 0xbfb8aa3b, v24
	v_mul_f32_e32 v25, 0xbfb8aa3b, v25
	v_mul_f32_e32 v26, 0xbfb8aa3b, v26
	v_mul_f32_e32 v27, 0xbfb8aa3b, v27
	v_exp_f32_e32 v28, v28
	v_exp_f32_e32 v29, v29
	v_exp_f32_e32 v30, v30
	v_exp_f32_e32 v31, v31
	v_exp_f32_e32 v24, v24
	v_exp_f32_e32 v25, v25
	v_exp_f32_e32 v26, v26
	v_exp_f32_e32 v27, v27
	v_add_f32_e32 v28, 1.0, v28
	v_add_f32_e32 v29, 1.0, v29
	v_add_f32_e32 v30, 1.0, v30
	v_add_f32_e32 v31, 1.0, v31
	v_add_f32_e32 v24, 1.0, v24
	v_add_f32_e32 v25, 1.0, v25
	v_add_f32_e32 v26, 1.0, v26
	v_add_f32_e32 v27, 1.0, v27
	v_min_f32_e32 v28, 0x7149f2ca, v28
	v_min_f32_e32 v29, 0x7149f2ca, v29
	v_min_f32_e32 v30, 0x7149f2ca, v30
	v_min_f32_e32 v31, 0x7149f2ca, v31
	v_min_f32_e32 v24, 0x7149f2ca, v24
	v_min_f32_e32 v25, 0x7149f2ca, v25
	v_min_f32_e32 v26, 0x7149f2ca, v26
	v_min_f32_e32 v27, 0x7149f2ca, v27
	v_cvt_pk_bf16_f32 v28, v28, v29
	v_cvt_pk_bf16_f32 v29, v30, v31
	v_cvt_pk_bf16_f32 v30, v24, v25
	v_cvt_pk_bf16_f32 v31, v26, v27
	v_mul_f32_e32 v76, 0xbfb8aa3b, v76
	v_mul_f32_e32 v77, 0xbfb8aa3b, v77
	v_mul_f32_e32 v78, 0xbfb8aa3b, v78
	v_mul_f32_e32 v79, 0xbfb8aa3b, v79
	v_mul_f32_e32 v72, 0xbfb8aa3b, v72
	v_mul_f32_e32 v73, 0xbfb8aa3b, v73
	v_mul_f32_e32 v74, 0xbfb8aa3b, v74
	v_mul_f32_e32 v75, 0xbfb8aa3b, v75
	v_exp_f32_e32 v76, v76
	v_exp_f32_e32 v77, v77
	v_exp_f32_e32 v78, v78
	v_exp_f32_e32 v79, v79
	v_exp_f32_e32 v72, v72
	v_exp_f32_e32 v73, v73
	v_exp_f32_e32 v74, v74
	v_exp_f32_e32 v75, v75
	v_add_f32_e32 v76, 1.0, v76
	v_add_f32_e32 v77, 1.0, v77
	v_add_f32_e32 v78, 1.0, v78
	v_add_f32_e32 v79, 1.0, v79
	v_add_f32_e32 v72, 1.0, v72
	v_add_f32_e32 v73, 1.0, v73
	v_add_f32_e32 v74, 1.0, v74
	v_add_f32_e32 v75, 1.0, v75
	v_min_f32_e32 v76, 0x7149f2ca, v76
	v_min_f32_e32 v77, 0x7149f2ca, v77
	v_min_f32_e32 v78, 0x7149f2ca, v78
	v_min_f32_e32 v79, 0x7149f2ca, v79
	v_min_f32_e32 v72, 0x7149f2ca, v72
	v_min_f32_e32 v73, 0x7149f2ca, v73
	v_min_f32_e32 v74, 0x7149f2ca, v74
	v_min_f32_e32 v75, 0x7149f2ca, v75
	v_cvt_pk_bf16_f32 v76, v76, v77
	v_cvt_pk_bf16_f32 v77, v78, v79
	v_cvt_pk_bf16_f32 v78, v72, v73
	v_cvt_pk_bf16_f32 v79, v74, v75
	v_mul_f32_e32 v20, 0xbfb8aa3b, v20
	v_mul_f32_e32 v21, 0xbfb8aa3b, v21
	v_mul_f32_e32 v22, 0xbfb8aa3b, v22
	v_mul_f32_e32 v23, 0xbfb8aa3b, v23
	v_mul_f32_e32 v16, 0xbfb8aa3b, v16
	v_mul_f32_e32 v17, 0xbfb8aa3b, v17
	v_mul_f32_e32 v18, 0xbfb8aa3b, v18
	v_mul_f32_e32 v19, 0xbfb8aa3b, v19
	v_exp_f32_e32 v20, v20
	v_exp_f32_e32 v21, v21
	v_exp_f32_e32 v22, v22
	v_exp_f32_e32 v23, v23
	v_exp_f32_e32 v16, v16
	v_exp_f32_e32 v17, v17
	v_exp_f32_e32 v18, v18
	v_exp_f32_e32 v19, v19
	v_add_f32_e32 v20, 1.0, v20
	v_add_f32_e32 v21, 1.0, v21
	v_add_f32_e32 v22, 1.0, v22
	v_add_f32_e32 v23, 1.0, v23
	v_add_f32_e32 v16, 1.0, v16
	v_add_f32_e32 v17, 1.0, v17
	v_add_f32_e32 v18, 1.0, v18
	v_add_f32_e32 v19, 1.0, v19
	v_min_f32_e32 v20, 0x7149f2ca, v20
	v_min_f32_e32 v21, 0x7149f2ca, v21
	v_min_f32_e32 v22, 0x7149f2ca, v22
	v_min_f32_e32 v23, 0x7149f2ca, v23
	v_min_f32_e32 v16, 0x7149f2ca, v16
	v_min_f32_e32 v17, 0x7149f2ca, v17
	v_min_f32_e32 v18, 0x7149f2ca, v18
	v_min_f32_e32 v19, 0x7149f2ca, v19
	v_cvt_pk_bf16_f32 v20, v20, v21
; __device__ __forceinline__ unsigned cvt_pk_bf16(float lo, float hi) { f32x2_t v = {lo, hi}; bf16x2_t b = __builtin_convertvector(v, bf16x2_t); return __builtin_bit_cast(unsigned, b); }
; #define EPI_FENCE() asm volatile("" ::: "memory")
; #define EPI_LANE() int t__ = threadIdx.x; asm volatile("" : "+v"(t__)); const int wid__ = __builtin_amdgcn_readfirstlane(t__ >> 6); wr = wid__ >> 2; wc = wid__ & 3; fr = t__ & 15; fq = (t__ & 63) >> 4
;     template <int MODE> __device__ __forceinline__ void run(const f32x4 (&acc)[2][2][4][2], const Unit& u, int wr, int wc, int fr, int fq) const {
;         EPI_LANE();
;         const int pn = u.pn, colt = pn * BM, t = colt >> 9;
;         char* base = (MODE == 2) ? (char*)(O + (size_t)6 * ((size_t)MTOK * 512)) + ((size_t)(((pn - 12) * 128 + u.pm) * 8 + wid__)) * 16384
;                                  : (char*)(O + (size_t)t * ((size_t)MTOK * 512) + (size_t)u.pm * BM * 512 + (colt & 511));
;         unsigned off0 = (MODE == 2) ? (unsigned)((t__ & 63) * 16) : (unsigned)((wr * 64 + fr) * 512 + wc * 32 + 8 * fq) * 2u; asm volatile("" : "+v"(off0));
; #pragma unroll
;         for (int bj = 0; bj < 2; ++bj) {
; #pragma unroll
;             for (int ai = 0; ai < 2; ++ai)
; #pragma unroll
;                 for (int m = 0; m < 4; ++m) { const unsigned off = off0 + ((MODE == 2) ? (unsigned)(((ai * 4 + m) * 2 + bj) * 1024) : (unsigned)((ai * HALF + m * 16) * 512 + bj * HALF) * 2u);
;                     const f32x4 v0 = acc[ai][bj][m][0], v1 = acc[ai][bj][m][1];
;                     u32x4 w; w.x = cvt_pk_bf16(actf<MODE>(v0[0]), actf<MODE>(v0[1])); w.y = cvt_pk_bf16(actf<MODE>(v0[2]), actf<MODE>(v0[3]));
;                     w.z = cvt_pk_bf16(actf<MODE>(v1[0]), actf<MODE>(v1[1])); w.w = cvt_pk_bf16(actf<MODE>(v1[2]), actf<MODE>(v1[3]));
;                     *(u32x4*)(base + off) = w; }
;             EPI_FENCE();
;         }
	v_cvt_pk_bf16_f32 v21, v22, v23
	v_cvt_pk_bf16_f32 v22, v16, v17
	v_cvt_pk_bf16_f32 v23, v18, v19
	v_mul_f32_e32 v12, 0xbfb8aa3b, v12
	v_mul_f32_e32 v13, 0xbfb8aa3b, v13
	v_mul_f32_e32 v14, 0xbfb8aa3b, v14
	v_mul_f32_e32 v15, 0xbfb8aa3b, v15
	v_mul_f32_e32 v8, 0xbfb8aa3b, v8
	v_mul_f32_e32 v9, 0xbfb8aa3b, v9
	v_mul_f32_e32 v10, 0xbfb8aa3b, v10
	v_mul_f32_e32 v11, 0xbfb8aa3b, v11
	v_exp_f32_e32 v12, v12
	v_exp_f32_e32 v13, v13
	v_exp_f32_e32 v14, v14
	v_exp_f32_e32 v15, v15
	v_exp_f32_e32 v8, v8
	v_exp_f32_e32 v9, v9
	v_exp_f32_e32 v10, v10
	v_exp_f32_e32 v11, v11
	v_add_f32_e32 v12, 1.0, v12
	v_add_f32_e32 v13, 1.0, v13
	v_add_f32_e32 v14, 1.0, v14
	v_add_f32_e32 v15, 1.0, v15
	v_add_f32_e32 v8, 1.0, v8
	v_add_f32_e32 v9, 1.0, v9
	v_add_f32_e32 v10, 1.0, v10
	v_add_f32_e32 v11, 1.0, v11
	v_min_f32_e32 v12, 0x7149f2ca, v12
	v_min_f32_e32 v13, 0x7149f2ca, v13
	v_min_f32_e32 v14, 0x7149f2ca, v14
	v_min_f32_e32 v15, 0x7149f2ca, v15
	v_min_f32_e32 v8, 0x7149f2ca, v8
	v_min_f32_e32 v9, 0x7149f2ca, v9
	v_min_f32_e32 v10, 0x7149f2ca, v10
	v_min_f32_e32 v11, 0x7149f2ca, v11
	v_cvt_pk_bf16_f32 v12, v12, v13
	v_cvt_pk_bf16_f32 v13, v14, v15
	v_cvt_pk_bf16_f32 v14, v8, v9
	v_cvt_pk_bf16_f32 v15, v10, v11
	v_mul_f32_e32 v4, 0xbfb8aa3b, v4
	v_mul_f32_e32 v5, 0xbfb8aa3b, v5
	v_mul_f32_e32 v6, 0xbfb8aa3b, v6
	v_mul_f32_e32 v7, 0xbfb8aa3b, v7
	v_mul_f32_e32 v0, 0xbfb8aa3b, v0
	v_mul_f32_e32 v1, 0xbfb8aa3b, v1
	v_mul_f32_e32 v2, 0xbfb8aa3b, v2
	v_mul_f32_e32 v3, 0xbfb8aa3b, v3
	v_exp_f32_e32 v4, v4
	v_exp_f32_e32 v5, v5
	v_exp_f32_e32 v6, v6
	v_exp_f32_e32 v7, v7
	v_exp_f32_e32 v0, v0
	v_exp_f32_e32 v1, v1
	v_exp_f32_e32 v2, v2
	v_exp_f32_e32 v3, v3
	v_add_f32_e32 v4, 1.0, v4
	v_add_f32_e32 v5, 1.0, v5
	v_add_f32_e32 v6, 1.0, v6
	v_add_f32_e32 v7, 1.0, v7
	v_add_f32_e32 v0, 1.0, v0
	v_add_f32_e32 v1, 1.0, v1
	v_add_f32_e32 v2, 1.0, v2
	v_add_f32_e32 v3, 1.0, v3
	v_min_f32_e32 v4, 0x7149f2ca, v4
	v_min_f32_e32 v5, 0x7149f2ca, v5
	v_min_f32_e32 v6, 0x7149f2ca, v6
	v_min_f32_e32 v7, 0x7149f2ca, v7
	v_min_f32_e32 v0, 0x7149f2ca, v0
	v_min_f32_e32 v1, 0x7149f2ca, v1
	v_min_f32_e32 v2, 0x7149f2ca, v2
	v_min_f32_e32 v3, 0x7149f2ca, v3
	v_cvt_pk_bf16_f32 v4, v4, v5
	v_cvt_pk_bf16_f32 v5, v6, v7
	v_cvt_pk_bf16_f32 v6, v0, v1
	v_cvt_pk_bf16_f32 v7, v2, v3
	v_permlane32_swap_b32_e32 v126, v92
	v_permlane32_swap_b32_e32 v127, v93
	v_permlane32_swap_b32_e32 v128, v94
	v_permlane32_swap_b32_e32 v129, v95
	v_permlane32_swap_b32_e32 v68, v36
	v_permlane32_swap_b32_e32 v69, v37
	v_permlane32_swap_b32_e32 v70, v38
	v_permlane32_swap_b32_e32 v71, v39
	v_permlane32_swap_b32_e32 v118, v84
	v_permlane32_swap_b32_e32 v119, v85
	v_permlane32_swap_b32_e32 v120, v86
	v_permlane32_swap_b32_e32 v121, v87
	v_permlane32_swap_b32_e32 v60, v28
	v_permlane32_swap_b32_e32 v61, v29
	v_permlane32_swap_b32_e32 v62, v30
	v_permlane32_swap_b32_e32 v63, v31
	v_permlane32_swap_b32_e32 v110, v76
	v_permlane32_swap_b32_e32 v111, v77
	v_permlane32_swap_b32_e32 v112, v78
	v_permlane32_swap_b32_e32 v113, v79
	v_permlane32_swap_b32_e32 v52, v20
	v_permlane32_swap_b32_e32 v53, v21
	v_permlane32_swap_b32_e32 v54, v22
	v_permlane32_swap_b32_e32 v55, v23
	v_permlane32_swap_b32_e32 v102, v12
	v_permlane32_swap_b32_e32 v103, v13
	v_permlane32_swap_b32_e32 v104, v14
	v_permlane32_swap_b32_e32 v105, v15
	v_permlane32_swap_b32_e32 v44, v4
	v_permlane32_swap_b32_e32 v45, v5
	v_permlane32_swap_b32_e32 v46, v6
	v_permlane32_swap_b32_e32 v47, v7
	v_permlane16_swap_b32_e32 v126, v110
	v_permlane16_swap_b32_e32 v127, v111
	v_permlane16_swap_b32_e32 v128, v112
	v_permlane16_swap_b32_e32 v129, v113
	v_permlane16_swap_b32_e32 v68, v52
	v_permlane16_swap_b32_e32 v69, v53
	v_permlane16_swap_b32_e32 v70, v54
	v_permlane16_swap_b32_e32 v71, v55
	v_permlane16_swap_b32_e32 v118, v102
	v_permlane16_swap_b32_e32 v119, v103
	v_permlane16_swap_b32_e32 v120, v104
	v_permlane16_swap_b32_e32 v121, v105
	v_permlane16_swap_b32_e32 v60, v44
	v_permlane16_swap_b32_e32 v61, v45
	v_permlane16_swap_b32_e32 v62, v46
	v_permlane16_swap_b32_e32 v63, v47
	v_permlane16_swap_b32_e32 v92, v76
	v_permlane16_swap_b32_e32 v93, v77
	v_permlane16_swap_b32_e32 v94, v78
	v_permlane16_swap_b32_e32 v95, v79
	v_permlane16_swap_b32_e32 v36, v20
	v_permlane16_swap_b32_e32 v37, v21
	v_permlane16_swap_b32_e32 v38, v22
	v_permlane16_swap_b32_e32 v39, v23
	v_permlane16_swap_b32_e32 v84, v12
	v_permlane16_swap_b32_e32 v85, v13
	v_permlane16_swap_b32_e32 v86, v14
	v_permlane16_swap_b32_e32 v87, v15
	v_permlane16_swap_b32_e32 v28, v4
	v_permlane16_swap_b32_e32 v29, v5
	v_permlane16_swap_b32_e32 v30, v6
	v_permlane16_swap_b32_e32 v31, v7
	v_mov_b32_e32 v160, v118
	v_mov_b32_e32 v161, v119
	v_mov_b32_e32 v162, v120
	v_mov_b32_e32 v163, v121
	v_mov_b32_dpp v118, v126 row_shl:8 row_mask:0xf bank_mask:0x3
	v_mov_b32_dpp v119, v127 row_shl:8 row_mask:0xf bank_mask:0x3
	v_mov_b32_dpp v120, v128 row_shl:8 row_mask:0xf bank_mask:0x3
	v_mov_b32_dpp v121, v129 row_shl:8 row_mask:0xf bank_mask:0x3
	v_mov_b32_dpp v126, v160 row_shr:8 row_mask:0xf bank_mask:0xc
	v_mov_b32_dpp v127, v161 row_shr:8 row_mask:0xf bank_mask:0xc
	v_mov_b32_dpp v128, v162 row_shr:8 row_mask:0xf bank_mask:0xc
	v_mov_b32_dpp v129, v163 row_shr:8 row_mask:0xf bank_mask:0xc
	v_mov_b32_e32 v160, v60
	v_mov_b32_e32 v161, v61
	v_mov_b32_e32 v162, v62
	v_mov_b32_e32 v163, v63
	v_mov_b32_dpp v60, v68 row_shl:8 row_mask:0xf bank_mask:0x3
	v_mov_b32_dpp v61, v69 row_shl:8 row_mask:0xf bank_mask:0x3
	v_mov_b32_dpp v62, v70 row_shl:8 row_mask:0xf bank_mask:0x3
	v_mov_b32_dpp v63, v71 row_shl:8 row_mask:0xf bank_mask:0x3
	v_mov_b32_dpp v68, v160 row_shr:8 row_mask:0xf bank_mask:0xc
; __device__ __forceinline__ unsigned cvt_pk_bf16(float lo, float hi) { f32x2_t v = {lo, hi}; bf16x2_t b = __builtin_convertvector(v, bf16x2_t); return __builtin_bit_cast(unsigned, b); }
; #define EPI_FENCE() asm volatile("" ::: "memory")
; #define EPI_LANE() int t__ = threadIdx.x; asm volatile("" : "+v"(t__)); const int wid__ = __builtin_amdgcn_readfirstlane(t__ >> 6); wr = wid__ >> 2; wc = wid__ & 3; fr = t__ & 15; fq = (t__ & 63) >> 4
;     template <int MODE> __device__ __forceinline__ void run(const f32x4 (&acc)[2][2][4][2], const Unit& u, int wr, int wc, int fr, int fq) const {
;         EPI_LANE();
;         const int pn = u.pn, colt = pn * BM, t = colt >> 9;
;         char* base = (MODE == 2) ? (char*)(O + (size_t)6 * ((size_t)MTOK * 512)) + ((size_t)(((pn - 12) * 128 + u.pm) * 8 + wid__)) * 16384
;                                  : (char*)(O + (size_t)t * ((size_t)MTOK * 512) + (size_t)u.pm * BM * 512 + (colt & 511));
;         unsigned off0 = (MODE == 2) ? (unsigned)((t__ & 63) * 16) : (unsigned)((wr * 64 + fr) * 512 + wc * 32 + 8 * fq) * 2u; asm volatile("" : "+v"(off0));
; #pragma unroll
;         for (int bj = 0; bj < 2; ++bj) {
; #pragma unroll
;             for (int ai = 0; ai < 2; ++ai)
; #pragma unroll
;                 for (int m = 0; m < 4; ++m) { const unsigned off = off0 + ((MODE == 2) ? (unsigned)(((ai * 4 + m) * 2 + bj) * 1024) : (unsigned)((ai * HALF + m * 16) * 512 + bj * HALF) * 2u);
;                     const f32x4 v0 = acc[ai][bj][m][0], v1 = acc[ai][bj][m][1];
;                     u32x4 w; w.x = cvt_pk_bf16(actf<MODE>(v0[0]), actf<MODE>(v0[1])); w.y = cvt_pk_bf16(actf<MODE>(v0[2]), actf<MODE>(v0[3]));
;                     w.z = cvt_pk_bf16(actf<MODE>(v1[0]), actf<MODE>(v1[1])); w.w = cvt_pk_bf16(actf<MODE>(v1[2]), actf<MODE>(v1[3]));
;                     *(u32x4*)(base + off) = w; }
;             EPI_FENCE();
;         }
	v_mov_b32_dpp v69, v161 row_shr:8 row_mask:0xf bank_mask:0xc
	v_mov_b32_dpp v70, v162 row_shr:8 row_mask:0xf bank_mask:0xc
	v_mov_b32_dpp v71, v163 row_shr:8 row_mask:0xf bank_mask:0xc
	v_mov_b32_e32 v160, v102
	v_mov_b32_e32 v161, v103
	v_mov_b32_e32 v162, v104
	v_mov_b32_e32 v163, v105
	v_mov_b32_dpp v102, v110 row_shl:8 row_mask:0xf bank_mask:0x3
	v_mov_b32_dpp v103, v111 row_shl:8 row_mask:0xf bank_mask:0x3
	v_mov_b32_dpp v104, v112 row_shl:8 row_mask:0xf bank_mask:0x3
	v_mov_b32_dpp v105, v113 row_shl:8 row_mask:0xf bank_mask:0x3
	v_mov_b32_dpp v110, v160 row_shr:8 row_mask:0xf bank_mask:0xc
	v_mov_b32_dpp v111, v161 row_shr:8 row_mask:0xf bank_mask:0xc
	v_mov_b32_dpp v112, v162 row_shr:8 row_mask:0xf bank_mask:0xc
	v_mov_b32_dpp v113, v163 row_shr:8 row_mask:0xf bank_mask:0xc
	v_mov_b32_e32 v160, v44
	v_mov_b32_e32 v161, v45
	v_mov_b32_e32 v162, v46
	v_mov_b32_e32 v163, v47
	v_mov_b32_dpp v44, v52 row_shl:8 row_mask:0xf bank_mask:0x3
	v_mov_b32_dpp v45, v53 row_shl:8 row_mask:0xf bank_mask:0x3
	v_mov_b32_dpp v46, v54 row_shl:8 row_mask:0xf bank_mask:0x3
	v_mov_b32_dpp v47, v55 row_shl:8 row_mask:0xf bank_mask:0x3
	v_mov_b32_dpp v52, v160 row_shr:8 row_mask:0xf bank_mask:0xc
	v_mov_b32_dpp v53, v161 row_shr:8 row_mask:0xf bank_mask:0xc
	v_mov_b32_dpp v54, v162 row_shr:8 row_mask:0xf bank_mask:0xc
	v_mov_b32_dpp v55, v163 row_shr:8 row_mask:0xf bank_mask:0xc
	v_mov_b32_e32 v160, v84
	v_mov_b32_e32 v161, v85
	v_mov_b32_e32 v162, v86
	v_mov_b32_e32 v163, v87
	v_mov_b32_dpp v84, v92 row_shl:8 row_mask:0xf bank_mask:0x3
	v_mov_b32_dpp v85, v93 row_shl:8 row_mask:0xf bank_mask:0x3
	v_mov_b32_dpp v86, v94 row_shl:8 row_mask:0xf bank_mask:0x3
	v_mov_b32_dpp v87, v95 row_shl:8 row_mask:0xf bank_mask:0x3
	v_mov_b32_dpp v92, v160 row_shr:8 row_mask:0xf bank_mask:0xc
	v_mov_b32_dpp v93, v161 row_shr:8 row_mask:0xf bank_mask:0xc
	v_mov_b32_dpp v94, v162 row_shr:8 row_mask:0xf bank_mask:0xc
	v_mov_b32_dpp v95, v163 row_shr:8 row_mask:0xf bank_mask:0xc
	v_mov_b32_e32 v160, v28
	v_mov_b32_e32 v161, v29
	v_mov_b32_e32 v162, v30
	v_mov_b32_e32 v163, v31
	v_mov_b32_dpp v28, v36 row_shl:8 row_mask:0xf bank_mask:0x3
	v_mov_b32_dpp v29, v37 row_shl:8 row_mask:0xf bank_mask:0x3
	v_mov_b32_dpp v30, v38 row_shl:8 row_mask:0xf bank_mask:0x3
	v_mov_b32_dpp v31, v39 row_shl:8 row_mask:0xf bank_mask:0x3
	v_mov_b32_dpp v36, v160 row_shr:8 row_mask:0xf bank_mask:0xc
	v_mov_b32_dpp v37, v161 row_shr:8 row_mask:0xf bank_mask:0xc
	v_mov_b32_dpp v38, v162 row_shr:8 row_mask:0xf bank_mask:0xc
	v_mov_b32_dpp v39, v163 row_shr:8 row_mask:0xf bank_mask:0xc
	v_mov_b32_e32 v160, v12
	v_mov_b32_e32 v161, v13
	v_mov_b32_e32 v162, v14
	v_mov_b32_e32 v163, v15
	v_mov_b32_dpp v12, v76 row_shl:8 row_mask:0xf bank_mask:0x3
	v_mov_b32_dpp v13, v77 row_shl:8 row_mask:0xf bank_mask:0x3
	v_mov_b32_dpp v14, v78 row_shl:8 row_mask:0xf bank_mask:0x3
	v_mov_b32_dpp v15, v79 row_shl:8 row_mask:0xf bank_mask:0x3
	v_mov_b32_dpp v76, v160 row_shr:8 row_mask:0xf bank_mask:0xc
	v_mov_b32_dpp v77, v161 row_shr:8 row_mask:0xf bank_mask:0xc
	v_mov_b32_dpp v78, v162 row_shr:8 row_mask:0xf bank_mask:0xc
	v_mov_b32_dpp v79, v163 row_shr:8 row_mask:0xf bank_mask:0xc
	v_mov_b32_e32 v160, v4
	v_mov_b32_e32 v161, v5
	v_mov_b32_e32 v162, v6
	v_mov_b32_e32 v163, v7
	v_mov_b32_dpp v4, v20 row_shl:8 row_mask:0xf bank_mask:0x3
	v_mov_b32_dpp v5, v21 row_shl:8 row_mask:0xf bank_mask:0x3
	v_mov_b32_dpp v6, v22 row_shl:8 row_mask:0xf bank_mask:0x3
	v_mov_b32_dpp v7, v23 row_shl:8 row_mask:0xf bank_mask:0x3
	v_mov_b32_dpp v20, v160 row_shr:8 row_mask:0xf bank_mask:0xc
	v_mov_b32_dpp v21, v161 row_shr:8 row_mask:0xf bank_mask:0xc
	v_mov_b32_dpp v22, v162 row_shr:8 row_mask:0xf bank_mask:0xc
	v_mov_b32_dpp v23, v163 row_shr:8 row_mask:0xf bank_mask:0xc
	v_mov_b32_e32 v160, v68
	v_mov_b32_e32 v161, v69
	v_mov_b32_e32 v162, v70
	v_mov_b32_e32 v163, v71
	v_mov_b32_dpp v68, v126 row_shl:4 row_mask:0xf bank_mask:0x5
	v_mov_b32_dpp v69, v127 row_shl:4 row_mask:0xf bank_mask:0x5
	v_mov_b32_dpp v70, v128 row_shl:4 row_mask:0xf bank_mask:0x5
	v_mov_b32_dpp v71, v129 row_shl:4 row_mask:0xf bank_mask:0x5
	v_mov_b32_dpp v126, v160 row_shr:4 row_mask:0xf bank_mask:0xa
	v_mov_b32_dpp v127, v161 row_shr:4 row_mask:0xf bank_mask:0xa
	v_mov_b32_dpp v128, v162 row_shr:4 row_mask:0xf bank_mask:0xa
	v_mov_b32_dpp v129, v163 row_shr:4 row_mask:0xf bank_mask:0xa
	v_mov_b32_e32 v160, v60
	v_mov_b32_e32 v161, v61
	v_mov_b32_e32 v162, v62
	v_mov_b32_e32 v163, v63
	v_mov_b32_dpp v60, v118 row_shl:4 row_mask:0xf bank_mask:0x5
	v_mov_b32_dpp v61, v119 row_shl:4 row_mask:0xf bank_mask:0x5
	v_mov_b32_dpp v62, v120 row_shl:4 row_mask:0xf bank_mask:0x5
	v_mov_b32_dpp v63, v121 row_shl:4 row_mask:0xf bank_mask:0x5
	v_mov_b32_dpp v118, v160 row_shr:4 row_mask:0xf bank_mask:0xa
; __device__ __forceinline__ unsigned cvt_pk_bf16(float lo, float hi) { f32x2_t v = {lo, hi}; bf16x2_t b = __builtin_convertvector(v, bf16x2_t); return __builtin_bit_cast(unsigned, b); }
; #define EPI_FENCE() asm volatile("" ::: "memory")
; #define EPI_LANE() int t__ = threadIdx.x; asm volatile("" : "+v"(t__)); const int wid__ = __builtin_amdgcn_readfirstlane(t__ >> 6); wr = wid__ >> 2; wc = wid__ & 3; fr = t__ & 15; fq = (t__ & 63) >> 4
;     template <int MODE> __device__ __forceinline__ void run(const f32x4 (&acc)[2][2][4][2], const Unit& u, int wr, int wc, int fr, int fq) const {
;         EPI_LANE();
;         const int pn = u.pn, colt = pn * BM, t = colt >> 9;
;         char* base = (MODE == 2) ? (char*)(O + (size_t)6 * ((size_t)MTOK * 512)) + ((size_t)(((pn - 12) * 128 + u.pm) * 8 + wid__)) * 16384
;                                  : (char*)(O + (size_t)t * ((size_t)MTOK * 512) + (size_t)u.pm * BM * 512 + (colt & 511));
;         unsigned off0 = (MODE == 2) ? (unsigned)((t__ & 63) * 16) : (unsigned)((wr * 64 + fr) * 512 + wc * 32 + 8 * fq) * 2u; asm volatile("" : "+v"(off0));
; #pragma unroll
;         for (int bj = 0; bj < 2; ++bj) {
; #pragma unroll
;             for (int ai = 0; ai < 2; ++ai)
; #pragma unroll
;                 for (int m = 0; m < 4; ++m) { const unsigned off = off0 + ((MODE == 2) ? (unsigned)(((ai * 4 + m) * 2 + bj) * 1024) : (unsigned)((ai * HALF + m * 16) * 512 + bj * HALF) * 2u);
;                     const f32x4 v0 = acc[ai][bj][m][0], v1 = acc[ai][bj][m][1];
;                     u32x4 w; w.x = cvt_pk_bf16(actf<MODE>(v0[0]), actf<MODE>(v0[1])); w.y = cvt_pk_bf16(actf<MODE>(v0[2]), actf<MODE>(v0[3]));
;                     w.z = cvt_pk_bf16(actf<MODE>(v1[0]), actf<MODE>(v1[1])); w.w = cvt_pk_bf16(actf<MODE>(v1[2]), actf<MODE>(v1[3]));
;                     *(u32x4*)(base + off) = w; }
;             EPI_FENCE();
;         }
	v_mov_b32_dpp v119, v161 row_shr:4 row_mask:0xf bank_mask:0xa
	v_mov_b32_dpp v120, v162 row_shr:4 row_mask:0xf bank_mask:0xa
	v_mov_b32_dpp v121, v163 row_shr:4 row_mask:0xf bank_mask:0xa
	v_mov_b32_e32 v160, v52
	v_mov_b32_e32 v161, v53
	v_mov_b32_e32 v162, v54
	v_mov_b32_e32 v163, v55
	v_mov_b32_dpp v52, v110 row_shl:4 row_mask:0xf bank_mask:0x5
	v_mov_b32_dpp v53, v111 row_shl:4 row_mask:0xf bank_mask:0x5
	v_mov_b32_dpp v54, v112 row_shl:4 row_mask:0xf bank_mask:0x5
	v_mov_b32_dpp v55, v113 row_shl:4 row_mask:0xf bank_mask:0x5
	v_mov_b32_dpp v110, v160 row_shr:4 row_mask:0xf bank_mask:0xa
	v_mov_b32_dpp v111, v161 row_shr:4 row_mask:0xf bank_mask:0xa
	v_mov_b32_dpp v112, v162 row_shr:4 row_mask:0xf bank_mask:0xa
	v_mov_b32_dpp v113, v163 row_shr:4 row_mask:0xf bank_mask:0xa
	v_mov_b32_e32 v160, v44
	v_mov_b32_e32 v161, v45
	v_mov_b32_e32 v162, v46
	v_mov_b32_e32 v163, v47
	v_mov_b32_dpp v44, v102 row_shl:4 row_mask:0xf bank_mask:0x5
	v_mov_b32_dpp v45, v103 row_shl:4 row_mask:0xf bank_mask:0x5
	v_mov_b32_dpp v46, v104 row_shl:4 row_mask:0xf bank_mask:0x5
	v_mov_b32_dpp v47, v105 row_shl:4 row_mask:0xf bank_mask:0x5
	v_mov_b32_dpp v102, v160 row_shr:4 row_mask:0xf bank_mask:0xa
	v_mov_b32_dpp v103, v161 row_shr:4 row_mask:0xf bank_mask:0xa
	v_mov_b32_dpp v104, v162 row_shr:4 row_mask:0xf bank_mask:0xa
	v_mov_b32_dpp v105, v163 row_shr:4 row_mask:0xf bank_mask:0xa
	v_mov_b32_e32 v160, v36
	v_mov_b32_e32 v161, v37
	v_mov_b32_e32 v162, v38
	v_mov_b32_e32 v163, v39
	v_mov_b32_dpp v36, v92 row_shl:4 row_mask:0xf bank_mask:0x5
	v_mov_b32_dpp v37, v93 row_shl:4 row_mask:0xf bank_mask:0x5
	v_mov_b32_dpp v38, v94 row_shl:4 row_mask:0xf bank_mask:0x5
	v_mov_b32_dpp v39, v95 row_shl:4 row_mask:0xf bank_mask:0x5
	v_mov_b32_dpp v92, v160 row_shr:4 row_mask:0xf bank_mask:0xa
	v_mov_b32_dpp v93, v161 row_shr:4 row_mask:0xf bank_mask:0xa
	v_mov_b32_dpp v94, v162 row_shr:4 row_mask:0xf bank_mask:0xa
	v_mov_b32_dpp v95, v163 row_shr:4 row_mask:0xf bank_mask:0xa
	v_mov_b32_e32 v160, v28
	v_mov_b32_e32 v161, v29
	v_mov_b32_e32 v162, v30
	v_mov_b32_e32 v163, v31
	v_mov_b32_dpp v28, v84 row_shl:4 row_mask:0xf bank_mask:0x5
	v_mov_b32_dpp v29, v85 row_shl:4 row_mask:0xf bank_mask:0x5
	v_mov_b32_dpp v30, v86 row_shl:4 row_mask:0xf bank_mask:0x5
	v_mov_b32_dpp v31, v87 row_shl:4 row_mask:0xf bank_mask:0x5
	v_mov_b32_dpp v84, v160 row_shr:4 row_mask:0xf bank_mask:0xa
	v_mov_b32_dpp v85, v161 row_shr:4 row_mask:0xf bank_mask:0xa
	v_mov_b32_dpp v86, v162 row_shr:4 row_mask:0xf bank_mask:0xa
	v_mov_b32_dpp v87, v163 row_shr:4 row_mask:0xf bank_mask:0xa
	v_mov_b32_e32 v160, v20
	v_mov_b32_e32 v161, v21
	v_mov_b32_e32 v162, v22
	v_mov_b32_e32 v163, v23
	v_mov_b32_dpp v20, v76 row_shl:4 row_mask:0xf bank_mask:0x5
	v_mov_b32_dpp v21, v77 row_shl:4 row_mask:0xf bank_mask:0x5
	v_mov_b32_dpp v22, v78 row_shl:4 row_mask:0xf bank_mask:0x5
	v_mov_b32_dpp v23, v79 row_shl:4 row_mask:0xf bank_mask:0x5
	v_mov_b32_dpp v76, v160 row_shr:4 row_mask:0xf bank_mask:0xa
	v_mov_b32_dpp v77, v161 row_shr:4 row_mask:0xf bank_mask:0xa
	v_mov_b32_dpp v78, v162 row_shr:4 row_mask:0xf bank_mask:0xa
	v_mov_b32_dpp v79, v163 row_shr:4 row_mask:0xf bank_mask:0xa
	v_mov_b32_e32 v160, v4
	v_mov_b32_e32 v161, v5
	v_mov_b32_e32 v162, v6
	v_mov_b32_e32 v163, v7
	v_mov_b32_dpp v4, v12 row_shl:4 row_mask:0xf bank_mask:0x5
	v_mov_b32_dpp v5, v13 row_shl:4 row_mask:0xf bank_mask:0x5
	v_mov_b32_dpp v6, v14 row_shl:4 row_mask:0xf bank_mask:0x5
	v_mov_b32_dpp v7, v15 row_shl:4 row_mask:0xf bank_mask:0x5
	v_mov_b32_dpp v12, v160 row_shr:4 row_mask:0xf bank_mask:0xa
	v_mov_b32_dpp v13, v161 row_shr:4 row_mask:0xf bank_mask:0xa
	v_mov_b32_dpp v14, v162 row_shr:4 row_mask:0xf bank_mask:0xa
	v_mov_b32_dpp v15, v163 row_shr:4 row_mask:0xf bank_mask:0xa
	v_and_b32_e32 v164, 0x3c, v212
	v_lshlrev_b32_e32 v164, 8, v164
	v_and_b32_e32 v165, 3, v212
	v_lshl_or_b32 v164, v165, 4, v164
	global_store_dwordx4 v164, v[126:129], s[54:55]
	global_store_dwordx4 v164, v[68:71], s[54:55] offset:64
	global_store_dwordx4 v164, v[118:121], s[54:55] offset:128
	global_store_dwordx4 v164, v[60:63], s[54:55] offset:192
	global_store_dwordx4 v164, v[110:113], s[54:55] offset:256
	global_store_dwordx4 v164, v[52:55], s[54:55] offset:320
	global_store_dwordx4 v164, v[102:105], s[54:55] offset:384
	global_store_dwordx4 v164, v[44:47], s[54:55] offset:448
	global_store_dwordx4 v164, v[92:95], s[54:55] offset:512
	global_store_dwordx4 v164, v[36:39], s[54:55] offset:576
	global_store_dwordx4 v164, v[84:87], s[54:55] offset:640
	global_store_dwordx4 v164, v[28:31], s[54:55] offset:704
	global_store_dwordx4 v164, v[76:79], s[54:55] offset:768
	global_store_dwordx4 v164, v[20:23], s[54:55] offset:832
	global_store_dwordx4 v164, v[12:15], s[54:55] offset:896
	global_store_dwordx4 v164, v[4:7], s[54:55] offset:960
